# combo15: combo11 + p->bf16 conversion moved out of the bandwidth-bound P0 phase into the attention phases (2 items per lane per attention unit, loads at unit start, convert+store at unit end)
# speedup vs baseline: 1.0122x; 1.0056x over previous
; __device__ __forceinline__ unsigned pk2(float lo, float hi) { f32x2_t v = {lo, hi}; bf16x2_t b = __builtin_convertvector(v, bf16x2_t); return __builtin_bit_cast(unsigned, b); }
; #define AIN(i) (kargs()->in[i])
; #define K_TID ((wave_s << 6) | lane_fresh())
; __global__ void __launch_bounds__(512, 2) fwd_megakernel(Args a) {
;     ...
;         const size_t n8 = (size_t)2 * T * PLED / 8; const float* pp_ = AIN(1); bf16_t* pb_ = P_PB;
;         for (size_t i = (size_t)bx * 512 + K_TID; i < n8; i += (size_t)G * 512) {
;             const f32x4 v0 = *(const f32x4*)(pp_ + 8 * i), v1 = *(const f32x4*)(pp_ + 8 * i + 4);
;             u32x4 w; w.x = pk2(v0[0], v0[1]); w.y = pk2(v0[2], v0[3]); w.z = pk2(v1[0], v1[1]); w.w = pk2(v1[2], v1[3]);
;             *(u32x4*)(pb_ + 8 * i) = w;
;         }
.LBB0_164:
	s_or_b64 exec, exec, s[0:1]
	s_mov_b64 s[4:5], s[46:47]
	s_mov_b64 s[6:7], s[46:47]
	s_ashr_i32 s75, s74, 31
	v_mbcnt_lo_u32_b32 v2, s2, 0
	v_mbcnt_hi_u32_b32 v2, s2, v2
	s_lshl_b64 s[0:1], s[74:75], 9
	v_or_b32_e32 v6, s82, v2
	v_ashrrev_i32_e32 v7, 31, v6
	v_lshl_add_u64 v[2:3], s[0:1], 0, v[6:7]
	s_mov_b64 s[0:1], 0x200000
	v_cmp_gt_u64_e32 vcc, s[0:1], v[2:3]
	s_and_saveexec_b64 s[0:1], vcc
	s_branch .LBB0_167
	s_load_dwordx2 s[2:3], s[4:5], 0x8
	s_load_dwordx2 s[8:9], s[6:7], 0x98
	s_load_dwordx2 s[10:11], s[46:47], 0xa0
	s_lshl_b64 s[6:7], s[74:75], 14
	v_lshlrev_b64 v[4:5], 5, v[6:7]
	s_mov_b64 s[12:13], 0x1fffff
	s_waitcnt lgkmcnt(0)
	s_ashr_i32 s11, s10, 31
	s_lshl_b64 s[4:5], s[10:11], 9
	s_add_u32 s2, s2, s6
	s_addc_u32 s3, s3, s7
	v_lshl_add_u64 v[4:5], s[2:3], 0, v[4:5]
	s_lshl_b64 s[6:7], s[10:11], 14
	s_lshl_b64 s[2:3], s[74:75], 13
	s_add_u32 s2, s8, s2
	s_addc_u32 s3, s9, s3
	v_lshl_add_u64 v[6:7], v[6:7], 4, s[2:3]
	s_mov_b64 s[2:3], 0x3804000
	v_lshl_add_u64 v[4:5], v[4:5], 0, 16
	v_lshl_add_u64 v[6:7], v[6:7], 0, s[2:3]
	s_lshl_b64 s[8:9], s[10:11], 13
	s_mov_b64 s[10:11], 0

; __device__ __forceinline__ float wave_sum(float v) { return xor32_sum(xor16_sum(row16_sum(v))); }
; #define AIN(i) (kargs()->in[i])
; #define K_TID ((wave_s << 6) | lane_fresh())
; #define K_LANE (lane_fresh())
; __global__ void __launch_bounds__(512, 2) fwd_megakernel(Args a) {
;     ...
;         for (size_t i = (size_t)bx * 512 + K_TID; i < n8; i += (size_t)G * 512) {
;     ...
;             int lane_l = K_LANE, tid_l = K_TID; asm volatile("" : "+v"(lane_l), "+v"(tid_l));
;             const float* gq = AIN(4) + l * 6 * 64;
;             float mg[6];
; #pragma unroll
;             for (int j = 0; j < 6; ++j) mg[j] = wave_max(fabsf(gq[j * 64 + lane_l]));
;             const float* rel = AIN(8) + l * 6 * 257;
;             float mr = 0.f;
;             for (int i = lane_l; i < 6 * 257; i += 64) mr = fmaxf(mr, fabsf(rel[i]));
;             mr = wave_max(mr);
;             const float* lp = AIN(5) + l * 4 * 64;
;             const float s01 = wave_sum(lp[lane_l] * lp[64 + lane_l]), s23 = wave_sum(lp[128 + lane_l] * lp[192 + lane_l]);
.Lprio_skip_1:
	s_mov_b32 s100, s74
	v_readlane_b32 s101, v251, 0
	s_nop 1
	s_lshl_b32 s100, s100, 9
	s_lshl_b32 s101, s101, 9
	v_mbcnt_lo_u32_b32 v212, -1, 0
	v_mbcnt_hi_u32_b32 v212, -1, v212
	v_or_b32_e32 v212, s82, v212
	v_add_u32_e32 v212, s100, v212
	v_mov_b32_e32 v211, s101
	s_cmp_lg_u32 s98, 0
	s_mov_b32 s0, -1
	v_mbcnt_lo_u32_b32 v0, s1, 0
	v_mbcnt_hi_u32_b32 v0, s1, v0
	s_mov_b64 s[2:3], s[46:47]
	v_mbcnt_lo_u32_b32 v1, s0, 0
	v_mbcnt_hi_u32_b32 v1, s0, v1
	s_mov_b64 s[0:1], s[46:47]
	v_or_b32_e32 v150, s82, v1
	s_load_dwordx2 s[0:1], s[0:1], 0x20
	v_ashrrev_i32_e32 v1, 31, v0
	v_lshlrev_b64 v[0:1], 2, v[0:1]
	v_mov_b32_e32 v8, 0
	v_mov_b32_e32 v12, 0
	s_waitcnt lgkmcnt(0)
	v_lshl_add_u64 v[2:3], s[0:1], 0, v[0:1]
	global_load_dword v4, v[2:3], off
	global_load_dword v5, v[2:3], off offset:256
	global_load_dword v6, v[2:3], off offset:512
	s_mov_b64 s[0:1], s[46:47]
	global_load_dword v2, v[2:3], off offset:768
	s_load_dwordx2 s[80:81], s[0:1], 0x40
	s_load_dwordx2 s[0:1], s[2:3], 0x28
	v_mov_b32_e32 v9, 0
	v_mov_b32_e32 v3, 0
	v_mov_b32_e32 v10, 0
	v_mov_b32_e32 v13, 0
	s_waitcnt lgkmcnt(0)
	v_lshl_add_u64 v[0:1], s[0:1], 0, v[0:1]
	global_load_dword v19, v[0:1], off
	global_load_dword v20, v[0:1], off offset:256
	global_load_dword v21, v[0:1], off offset:512
	global_load_dword v22, v[0:1], off offset:768
	v_mov_b32_e32 v16, 0
	v_mov_b32_e32 v11, 0
	v_mov_b32_e32 v14, 0
	v_mov_b32_e32 v17, 0
	v_mov_b32_e32 v15, 0
	v_mov_b32_e32 v18, 0
	v_mov_b32_e32 v7, 0
	s_mov_b64 s[0:1], s[46:47]
	s_mov_b32 s2, 0x3fb8aa3b
	s_load_dwordx2 s[0:1], s[0:1], 0x98
	s_waitcnt lgkmcnt(0)
	v_writelane_b32 v251, s0, 15
	s_nop 1
	v_writelane_b32 v251, s1, 16
	s_mov_b64 s[0:1], s[46:47]
	s_load_dwordx2 s[4:5], s[0:1], 0x98
	s_mov_b64 s[0:1], s[46:47]
	s_load_dwordx2 s[6:7], s[0:1], 0x98
	s_mov_b64 s[0:1], s[46:47]
	s_load_dwordx2 s[20:21], s[0:1], 0x30
	s_mov_b32 s0, 0xc2ce8ed0
	s_mov_b32 s1, 0x42b17218
	s_waitcnt vmcnt(7)
	v_and_b32_e32 v0, 0x7fffffff, v4
	s_nop 1
	v_mov_b32_dpp v8, v0 quad_perm:[1,0,3,2] row_mask:0xf bank_mask:0xf
	v_max_f32_e64 v1, |v4|, |v4|
	s_waitcnt vmcnt(6)
	v_and_b32_e32 v4, 0x7fffffff, v5
	v_max_f32_e32 v0, v8, v8
	v_max_f32_e32 v0, v1, v0
	v_mov_b32_dpp v12, v4 quad_perm:[1,0,3,2] row_mask:0xf bank_mask:0xf
	v_max_f32_e64 v5, |v5|, |v5|
	v_max_f32_e32 v4, v12, v12
	v_mov_b32_dpp v9, v0 quad_perm:[2,3,0,1] row_mask:0xf bank_mask:0xf
	s_waitcnt vmcnt(5)
	v_and_b32_e32 v23, 0x7fffffff, v6
	v_max_f32_e32 v1, v5, v4
	v_max_f32_e32 v4, v9, v9
	v_mov_b32_dpp v3, v23 quad_perm:[1,0,3,2] row_mask:0xf bank_mask:0xf
	v_max_f32_e32 v0, v0, v4
	v_max_f32_e64 v6, |v6|, |v6|
	v_max_f32_e32 v3, v3, v3
	v_mov_b32_dpp v10, v0 row_half_mirror row_mask:0xf bank_mask:0xf
	v_max_f32_e32 v3, v6, v3
	v_max_f32_e32 v4, v10, v10
	v_mov_b32_dpp v13, v1 quad_perm:[2,3,0,1] row_mask:0xf bank_mask:0xf
	v_mov_b32_dpp v16, v3 quad_perm:[2,3,0,1] row_mask:0xf bank_mask:0xf
	v_max_f32_e32 v0, v0, v4
	v_max_f32_e32 v5, v13, v13
	v_max_f32_e32 v6, v16, v16
	v_mov_b32_dpp v11, v0 row_mirror row_mask:0xf bank_mask:0xf
	v_max_f32_e32 v1, v1, v5
	v_max_f32_e32 v3, v3, v6
	v_max_f32_e32 v4, v11, v11
	v_mov_b32_dpp v14, v1 row_half_mirror row_mask:0xf bank_mask:0xf
	v_mov_b32_dpp v17, v3 row_half_mirror row_mask:0xf bank_mask:0xf
	v_max_f32_e32 v0, v0, v4
	v_max_f32_e32 v5, v14, v14
	v_max_f32_e32 v6, v17, v17
	v_mov_b32_e32 v4, v0
	v_max_f32_e32 v1, v1, v5
	v_max_f32_e32 v3, v3, v6
	v_permlane16_swap_b32_e32 v0, v4
	v_mov_b32_dpp v15, v1 row_mirror row_mask:0xf bank_mask:0xf
	v_mov_b32_dpp v18, v3 row_mirror row_mask:0xf bank_mask:0xf
	v_max_f32_e32 v4, v4, v4
	v_max_f32_e32 v0, v0, v0
	v_max_f32_e32 v5, v15, v15
	v_max_f32_e32 v6, v18, v18
	v_max_f32_e32 v0, v0, v4
	v_max_f32_e32 v1, v1, v5
	v_max_f32_e32 v3, v3, v6
	v_mov_b32_e32 v4, v0
	v_mov_b32_e32 v5, v1
	v_mov_b32_e32 v6, v3
	v_permlane32_swap_b32_e32 v0, v4
	v_permlane16_swap_b32_e32 v1, v5
	v_max_f32_e32 v4, v4, v4
	v_max_f32_e32 v0, v0, v0
	v_permlane16_swap_b32_e32 v3, v6
	v_max_f32_e32 v5, v5, v5
	v_max_f32_e32 v1, v1, v1
	v_max_f32_e32 v0, v0, v4
	v_max_f32_e32 v4, v6, v6
	v_max_f32_e32 v3, v3, v3
	v_max_f32_e32 v1, v1, v5
	v_max_f32_e32 v3, v3, v4
	v_mov_b32_e32 v5, v1
	v_mov_b32_e32 v4, v3
	s_nop 0
	v_permlane32_swap_b32_e32 v1, v5
	v_permlane32_swap_b32_e32 v3, v4
	v_max_f32_e32 v5, v5, v5
	v_max_f32_e32 v1, v1, v1
	v_max_f32_e32 v4, v4, v4
	v_max_f32_e32 v3, v3, v3
	v_max_f32_e32 v1, v1, v5
	v_max_f32_e32 v3, v3, v4
	s_waitcnt vmcnt(4)
; #define LAS __attribute__((address_space(3)))
; __device__ __forceinline__ float wave_sum(float v) { return xor32_sum(xor16_sum(row16_sum(v))); }
; #define AIN(i) (kargs()->in[i])
; #define AWS (kargs()->ws)
;             #define RFL(x) __uint_as_float(__builtin_amdgcn_readfirstlane(__float_as_uint(x)))
; __device__ __forceinline__ void attn_phase(const AttnCtx& C, unsigned* counter, LAS unsigned char* lds, int tid) {
;     LAS unsigned* ub = (LAS unsigned*)(lds + AL_U);
;     __syncthreads();
;     if (tid == 0) ub[0] = atomicAdd(counter, 1u);
; __global__ void __launch_bounds__(512, 2) fwd_megakernel(Args a) {
;     ...
;             for (int j = 0; j < 6; ++j) mg[j] = wave_max(fabsf(gq[j * 64 + lane_l]));
;             const float* rel = AIN(8) + l * 6 * 257;
;             float mr = 0.f;
;             for (int i = lane_l; i < 6 * 257; i += 64) mr = fmaxf(mr, fabsf(rel[i]));
;             mr = wave_max(mr);
;             const float* lp = AIN(5) + l * 4 * 64;
;             const float s01 = wave_sum(lp[lane_l] * lp[64 + lane_l]), s23 = wave_sum(lp[128 + lane_l] * lp[192 + lane_l]);
;             const float lam_init = (l == 0) ? 0.2f : (0.8f - 0.6f * 0.7408182206817179f);
;             AttnCtx C;
;             C.Z = P_Zb; C.O = P_HN; C.F2 = P_F2; C.rel = rel; C.subln = AIN(6) + l * 64;
;             C.lam = expf(s01) - expf(s23) + lam_init; C.oml = 1.0f - lam_init;
;             C.Mb0 = 8.0f * mg[0] * mg[1] * LOG2E * 1.02f + 1.0f; C.Mb1 = 8.0f * mg[2] * mg[3] * LOG2E * 1.02f + 1.0f; C.Mb2 = 8.0f * mg[4] * mg[5] * LOG2E * 1.02f + 1.0f + mr * LOG2E;
;     ...
;             C.lam = RFL(C.lam); C.oml = RFL(C.oml); C.Mb0 = RFL(C.Mb0); C.Mb1 = RFL(C.Mb1); C.Mb2 = RFL(C.Mb2);
;             attn_phase(C, (unsigned*)(AWS + WS_CTL) + CTL_Q + 16 * (1 + l), lds, tid_l);
	v_and_b32_e32 v4, 0x7fffffff, v2
	v_mov_b32_e32 v5, 0
	v_max_f32_e64 v2, |v2|, |v2|
	v_mul_f32_e32 v0, 0x41000000, v0
	v_mov_b32_dpp v5, v4 quad_perm:[1,0,3,2] row_mask:0xf bank_mask:0xf
	v_max_f32_e32 v4, v5, v5
	v_max_f32_e32 v2, v2, v4
	v_mov_b32_e32 v4, 0
	v_mov_b32_e32 v5, 0
	v_mul_f32_e32 v0, v0, v1
	v_mov_b32_dpp v4, v2 quad_perm:[2,3,0,1] row_mask:0xf bank_mask:0xf
	v_max_f32_e32 v4, v4, v4
	v_max_f32_e32 v2, v2, v4
	v_mov_b32_e32 v4, 0
	v_mul_f32_e32 v1, 0x41000000, v3
	v_readfirstlane_b32 s3, v0
	v_mov_b32_dpp v4, v2 row_half_mirror row_mask:0xf bank_mask:0xf
	v_max_f32_e32 v4, v4, v4
	v_max_f32_e32 v2, v2, v4
	v_mov_b32_e32 v4, 0
	s_nop 1
	v_mov_b32_dpp v4, v2 row_mirror row_mask:0xf bank_mask:0xf
	v_max_f32_e32 v4, v4, v4
	v_max_f32_e32 v2, v2, v4
	v_mov_b32_e32 v4, v2
	s_nop 1
	v_permlane16_swap_b32_e32 v2, v4
	v_max_f32_e32 v4, v4, v4
	v_max_f32_e32 v2, v2, v2
	v_max_f32_e32 v2, v2, v4
	v_mov_b32_e32 v4, v2
	s_nop 1
	v_permlane32_swap_b32_e32 v2, v4
	v_max_f32_e32 v4, v4, v4
	v_max_f32_e32 v2, v2, v2
	v_max_f32_e32 v2, v2, v4
	s_waitcnt vmcnt(2)
	v_mul_f32_e32 v4, v19, v20
	v_mul_f32_e32 v1, v1, v2
	s_nop 0
	v_mov_b32_dpp v5, v4 quad_perm:[1,0,3,2] row_mask:0xf bank_mask:0xf
	v_fmac_f32_e32 v5, v19, v20
	s_nop 1
	v_add_f32_dpp v4, v5, v5 quad_perm:[2,3,0,1] row_mask:0xf bank_mask:0xf bound_ctrl:1
	s_nop 1
	v_add_f32_dpp v4, v4, v4 row_half_mirror row_mask:0xf bank_mask:0xf bound_ctrl:1
	s_nop 1
	v_add_f32_dpp v4, v4, v4 row_mirror row_mask:0xf bank_mask:0xf bound_ctrl:1
	v_mov_b32_e32 v5, v4
	s_nop 1
	v_permlane16_swap_b32_e32 v4, v5
	v_add_f32_e32 v4, v4, v5
	v_mov_b32_e32 v5, v4
	s_nop 1
	v_permlane32_swap_b32_e32 v4, v5
	v_add_f32_e32 v4, v4, v5
	s_waitcnt vmcnt(0)
	v_mul_f32_e32 v5, v21, v22
	v_cmp_ngt_f32_e32 vcc, s0, v4
	s_nop 0
	v_mov_b32_dpp v7, v5 quad_perm:[1,0,3,2] row_mask:0xf bank_mask:0xf
	v_fmac_f32_e32 v7, v21, v22
	s_nop 1
	v_add_f32_dpp v5, v7, v7 quad_perm:[2,3,0,1] row_mask:0xf bank_mask:0xf bound_ctrl:1
	s_nop 1
	v_add_f32_dpp v5, v5, v5 row_half_mirror row_mask:0xf bank_mask:0xf bound_ctrl:1
	s_nop 1
	v_add_f32_dpp v5, v5, v5 row_mirror row_mask:0xf bank_mask:0xf bound_ctrl:1
	v_mov_b32_e32 v6, v5
	s_nop 1
	v_permlane16_swap_b32_e32 v5, v6
	v_add_f32_e32 v5, v5, v6
	v_mov_b32_e32 v6, v5
	s_nop 1
	v_permlane32_swap_b32_e32 v5, v6
	v_add_f32_e32 v5, v5, v6
	v_mul_f32_e32 v6, 0x3fb8aa3b, v4
	v_fma_f32 v7, v4, s2, -v6
	v_rndne_f32_e32 v8, v6
	v_fmac_f32_e32 v7, 0x32a5705f, v4
	v_sub_f32_e32 v6, v6, v8
	v_add_f32_e32 v6, v6, v7
	v_exp_f32_e32 v6, v6
	v_cvt_i32_f32_e32 v7, v8
	v_ldexp_f32 v6, v6, v7
	v_mul_f32_e32 v7, 0x3fb8aa3b, v5
	v_fma_f32 v8, v5, s2, -v7
	v_rndne_f32_e32 v9, v7
	v_fmac_f32_e32 v8, 0x32a5705f, v5
	v_sub_f32_e32 v7, v7, v9
	v_add_f32_e32 v7, v7, v8
	v_exp_f32_e32 v7, v7
	v_cvt_i32_f32_e32 v8, v9
	v_cndmask_b32_e32 v6, 0, v6, vcc
	v_mov_b32_e32 v9, 0x7f800000
	v_cmp_nlt_f32_e32 vcc, s1, v4
	v_readfirstlane_b32 s2, v1
	s_nop 0
	v_cndmask_b32_e32 v4, v9, v6, vcc
	v_ldexp_f32 v6, v7, v8
	v_cmp_ngt_f32_e32 vcc, s0, v5
	s_nop 1
	v_cndmask_b32_e32 v6, 0, v6, vcc
	v_cmp_nlt_f32_e32 vcc, s1, v5
	s_mov_b64 s[0:1], s[46:47]
	s_load_dwordx2 s[0:1], s[0:1], 0x98
	v_cndmask_b32_e32 v5, v9, v6, vcc
	v_sub_f32_e32 v4, v4, v5
	v_cmp_eq_u32_e32 vcc, 0, v150
	v_readfirstlane_b32 s12, v4
	s_waitcnt lgkmcnt(0)
	s_add_u32 s0, s0, 0x3840
	s_addc_u32 s1, s1, 0
	v_writelane_b32 v251, s0, 17
	s_barrier
	s_nop 0
	v_writelane_b32 v251, s1, 18
	s_and_saveexec_b64 s[0:1], vcc
	s_cbranch_execz .LBB0_349
	s_mov_b64 s[10:11], exec
	v_mbcnt_lo_u32_b32 v0, s10, 0
	v_mbcnt_hi_u32_b32 v0, s11, v0
	v_cmp_eq_u32_e32 vcc, 0, v0
	s_and_saveexec_b64 s[8:9], vcc
	s_cbranch_execz .LBB0_348
	s_bcnt1_i32_b64 s10, s[10:11]
	v_mov_b32_e32 v2, s10
	v_readlane_b32 s10, v251, 17
	v_mov_b32_e32 v1, 0
	v_readlane_b32 s11, v251, 18
	s_nop 4
	global_atomic_add v1, v1, v2, s[10:11] sc0

; __device__ __forceinline__ unsigned pk2(float lo, float hi) { f32x2_t v = {lo, hi}; bf16x2_t b = __builtin_convertvector(v, bf16x2_t); return __builtin_bit_cast(unsigned, b); }
; __device__ __forceinline__ void attn_phase(const AttnCtx& C, unsigned* counter, LAS unsigned char* lds, int tid) {
;     ...
;     if (tid == 0) ub[0] = atomicAdd(counter, 1u);
;     for (;;) {
;         __syncthreads();
; __global__ void __launch_bounds__(512, 2) fwd_megakernel(Args a) {
;     ...
;             const f32x4 v0 = *(const f32x4*)(pp_ + 8 * i), v1 = *(const f32x4*)(pp_ + 8 * i + 4);
;             u32x4 w; w.x = pk2(v0[0], v0[1]); w.y = pk2(v0[2], v0[3]); w.z = pk2(v1[0], v1[1]); w.w = pk2(v1[2], v1[3]);
;             *(u32x4*)(pb_ + 8 * i) = w;
.LBB0_350:
	s_or_b64 exec, exec, s[0:1]
	s_load_dwordx2 s[100:101], s[46:47], 0x98
	s_waitcnt lgkmcnt(0)
	s_add_u32 s100, s100, 0x3804000
	s_addc_u32 s101, s101, 0
	s_waitcnt vmcnt(40)
	v_cmp_gt_u32_e32 vcc, 0x100000, v248
	s_and_saveexec_b64 s[98:99], vcc
	v_cvt_pk_bf16_f32 v232, v232, v233
	v_cvt_pk_bf16_f32 v233, v234, v235
	v_cvt_pk_bf16_f32 v234, v236, v237
	v_cvt_pk_bf16_f32 v235, v238, v239
	v_lshlrev_b32_e32 v250, 4, v248
	global_store_dwordx4 v250, v[232:235], s[100:101]
	s_mov_b64 exec, s[98:99]
	v_cmp_gt_u32_e32 vcc, 0x100000, v249
	s_and_saveexec_b64 s[98:99], vcc
	v_cvt_pk_bf16_f32 v240, v240, v241
	v_cvt_pk_bf16_f32 v241, v242, v243
	v_cvt_pk_bf16_f32 v242, v244, v245
	v_cvt_pk_bf16_f32 v243, v246, v247
	v_lshlrev_b32_e32 v250, 4, v249
	global_store_dwordx4 v250, v[240:243], s[100:101]
	s_mov_b64 exec, s[98:99]
	s_mov_b64 s[0:1], 0

; #define K_TID ((wave_s << 6) | lane_fresh())
; __device__ __forceinline__ void attn_phase(const AttnCtx& C, unsigned* counter, LAS unsigned char* lds, int tid) {
;     ...
;         __syncthreads();
;         const int u = (int)ub[0];
;         if (u >= ATT_UNITS) break;
;         int ty, ub_, uh, uq;
;         if (u < 256) { ty = 0; ub_ = (u & 31) >> 2; uh = u & 3; uq = 15 - (u >> 5); }
;         else if (u < 1280) { const int v = u - 256, q = 7 - (v >> 7), wv = v & 127;
;             if (wv < 32) { ty = 0; ub_ = wv >> 2; uh = wv & 3; uq = q; }
;             else if (wv < 80) { ty = 1; ub_ = (wv - 32) / 6; uh = (wv - 32) % 6; uq = 2 * q + 1; }
;             else { ty = 1; ub_ = (wv - 80) / 6; uh = (wv - 80) % 6; uq = 2 * q; } }
;         else { const int v = u - 1280; ty = 2; ub_ = (v % 48) / 6; uh = (v % 48) % 6; uq = 15 - v / 48; }
; __global__ void __launch_bounds__(512, 2) fwd_megakernel(Args a) {
;     ...
;         for (size_t i = (size_t)bx * 512 + K_TID; i < n8; i += (size_t)G * 512) {
;             const f32x4 v0 = *(const f32x4*)(pp_ + 8 * i), v1 = *(const f32x4*)(pp_ + 8 * i + 4);
.LBB0_352:
	s_waitcnt lgkmcnt(0)
	s_barrier
	ds_read_b32 v0, v154
	s_movk_i32 s0, 0x7ff
	s_waitcnt lgkmcnt(0)
	v_cmp_lt_i32_e32 vcc, s0, v0
	v_readfirstlane_b32 s2, v0
	s_mov_b64 s[0:1], -1
	s_cbranch_vccnz .LBB0_351
	s_load_dwordx2 s[100:101], s[46:47], 0x8
	v_mov_b32_e32 v248, v212
	v_add_u32_e32 v249, v212, v211
	v_add_u32_e32 v212, v249, v211
	v_cmp_gt_u32_e32 vcc, 0x100000, v248
	s_waitcnt lgkmcnt(0)
	s_and_saveexec_b64 s[98:99], vcc
	v_lshlrev_b32_e32 v250, 5, v248
	global_load_dwordx4 v[232:235], v250, s[100:101]
	global_load_dwordx4 v[236:239], v250, s[100:101] offset:16
	s_mov_b64 exec, s[98:99]
	v_cmp_gt_u32_e32 vcc, 0x100000, v249
	s_and_saveexec_b64 s[98:99], vcc
	v_lshlrev_b32_e32 v250, 5, v249
	global_load_dwordx4 v[240:243], v250, s[100:101]
	global_load_dwordx4 v[244:247], v250, s[100:101] offset:16
	s_mov_b64 exec, s[98:99]
	s_cmpk_gt_i32 s2, 0xff
	s_mov_b64 s[4:5], -1
	s_cbranch_scc0 .LBB0_366
	s_cmpk_gt_u32 s2, 0x4ff
	s_cbranch_scc0 .LBB0_356
	s_add_i32 s0, s2, 0xfb00
	s_and_b32 s1, s0, 0xffff
	s_mul_i32 s1, s1, 0xaaab
	s_lshr_b32 s1, s1, 21
	s_mul_i32 s4, s1, 48
	s_sub_i32 s0, s0, s4
	s_mul_i32 s4, s0, 0xab
	s_bfe_u32 s24, s4, 0x6000a
	s_mul_i32 s4, s24, 6
	s_sub_i32 s0, s0, s4
	s_and_b32 s78, s0, 0xff
	s_sub_i32 s7, 15, s1
	s_mov_b64 s[4:5], 0

; __device__ __forceinline__ unsigned pk2(float lo, float hi) { f32x2_t v = {lo, hi}; bf16x2_t b = __builtin_convertvector(v, bf16x2_t); return __builtin_bit_cast(unsigned, b); }
; #define K_TID ((wave_s << 6) | lane_fresh())
; __device__ __forceinline__ void xcd_barrier(const XcdBarrier& b, const bool xb_is_leader) {
;     asm volatile("s_waitcnt vmcnt(0)" ::: "memory");
;     __syncthreads();
;     if (xb_is_leader) {
;         unsigned* bar = b.bar;
;         __builtin_amdgcn_s_waitcnt(0);
;         unsigned nloc = b.st[0], nx = b.st[1];
;         if (nloc == 0u) { xcd_barrier_complete(bar, b.x, nloc, nx); b.st[0] = nloc; b.st[1] = nx; }
; __global__ void __launch_bounds__(512, 2) fwd_megakernel(Args a) {
;     ...
;         for (size_t i = (size_t)bx * 512 + K_TID; i < n8; i += (size_t)G * 512) {
;             const f32x4 v0 = *(const f32x4*)(pp_ + 8 * i), v1 = *(const f32x4*)(pp_ + 8 * i + 4);
;             u32x4 w; w.x = pk2(v0[0], v0[1]); w.y = pk2(v0[2], v0[3]); w.z = pk2(v1[0], v1[1]); w.w = pk2(v1[2], v1[3]);
;             *(u32x4*)(pb_ + 8 * i) = w;
.LBB0_462:
.Lpd_rem_0:
	v_cmp_gt_u32_e32 vcc, 0x100000, v212
	s_and_saveexec_b64 s[98:99], vcc
	s_cbranch_execz .Lpd_done_0
	s_load_dwordx2 s[100:101], s[46:47], 0x8
	v_lshlrev_b32_e32 v250, 5, v212
	s_waitcnt lgkmcnt(0)
	global_load_dwordx4 v[232:235], v250, s[100:101]
	global_load_dwordx4 v[236:239], v250, s[100:101] offset:16
	s_load_dwordx2 s[100:101], s[46:47], 0x98
	s_waitcnt lgkmcnt(0)
	s_add_u32 s100, s100, 0x3804000
	s_addc_u32 s101, s101, 0
	s_waitcnt vmcnt(0)
	v_cvt_pk_bf16_f32 v232, v232, v233
	v_cvt_pk_bf16_f32 v233, v234, v235
	v_cvt_pk_bf16_f32 v234, v236, v237
	v_cvt_pk_bf16_f32 v235, v238, v239
	v_lshlrev_b32_e32 v250, 4, v212
	global_store_dwordx4 v250, v[232:235], s[100:101]
	v_add_u32_e32 v212, v212, v211
	s_mov_b64 exec, s[98:99]
	s_branch .Lpd_rem_0
.Lpd_done_0:
	s_mov_b64 exec, s[98:99]
	s_mov_b32 s0, -1
	s_nop 0
	v_mbcnt_lo_u32_b32 v0, s0, 0
	v_mbcnt_hi_u32_b32 v0, s0, v0
	s_setprio 0
	s_waitcnt vmcnt(0)
	s_waitcnt lgkmcnt(0)
	v_or_b32_e32 v0, s82, v0
	v_cmp_eq_u32_e32 vcc, 0, v0
	s_barrier
	s_and_saveexec_b64 s[4:5], vcc
	v_readlane_b32 s86, v251, 19
	v_readlane_b32 s87, v251, 20
	s_cbranch_execz .LBB0_514
	v_mov_b32_e32 v0, 0x22000
	s_waitcnt vmcnt(0) expcnt(0) lgkmcnt(0)
	ds_read_b32 v2, v0
	v_mov_b32_e32 v0, 0x22004
	ds_read_b32 v0, v0
	s_waitcnt lgkmcnt(1)
	v_cmp_ne_u32_e32 vcc, 0, v2
	s_cbranch_vccnz .LBB0_478
	v_readlane_b32 s0, v251, 0
	v_readlane_b32 s1, v251, 1
	v_readlane_b32 s2, v251, 2
	s_mul_i32 s2, s1, s2
	s_mul_i32 s2, s2, s0
	s_add_u32 s0, s76, 0x1000
	s_addc_u32 s1, s77, 0
	s_add_u32 s6, s76, 0x1100
	s_addc_u32 s7, s77, 0
	s_add_u32 s8, s76, 0x1200
	s_addc_u32 s9, s77, 0
	s_add_u32 s10, s76, 0x1300
	s_addc_u32 s11, s77, 0
	s_mov_b32 s3, 1
	v_mov_b32_e32 v16, 0
	s_branch .LBB0_466

; __device__ __forceinline__ float wave_sum(float v) { return xor32_sum(xor16_sum(row16_sum(v))); }
; #define AIN(i) (kargs()->in[i])
; #define K_TID ((wave_s << 6) | lane_fresh())
; #define K_LANE (lane_fresh())
; __global__ void __launch_bounds__(512, 2) fwd_megakernel(Args a) {
;     ...
;         for (size_t i = (size_t)bx * 512 + K_TID; i < n8; i += (size_t)G * 512) {
;     ...
;             int lane_l = K_LANE, tid_l = K_TID; asm volatile("" : "+v"(lane_l), "+v"(tid_l));
;             const float* gq = AIN(4) + l * 6 * 64;
;             float mg[6];
; #pragma unroll
;             for (int j = 0; j < 6; ++j) mg[j] = wave_max(fabsf(gq[j * 64 + lane_l]));
;             const float* rel = AIN(8) + l * 6 * 257;
;             float mr = 0.f;
;             for (int i = lane_l; i < 6 * 257; i += 64) mr = fmaxf(mr, fabsf(rel[i]));
;             mr = wave_max(mr);
;             const float* lp = AIN(5) + l * 4 * 64;
;             const float s01 = wave_sum(lp[lane_l] * lp[64 + lane_l]), s23 = wave_sum(lp[128 + lane_l] * lp[192 + lane_l]);
.Lprio_skip_2:
	v_readlane_b32 s100, v251, 19
	v_readlane_b32 s101, v251, 0
	s_nop 1
	s_lshl_b32 s100, s100, 9
	s_lshl_b32 s101, s101, 9
	s_add_u32 s100, s100, 0x100000
	v_mbcnt_lo_u32_b32 v212, -1, 0
	v_mbcnt_hi_u32_b32 v212, -1, v212
	v_or_b32_e32 v212, s82, v212
	v_add_u32_e32 v212, s100, v212
	v_mov_b32_e32 v211, s101
	s_cmp_lg_u32 s98, 0
	s_mov_b32 s0, -1
	v_mbcnt_lo_u32_b32 v0, s1, 0
	v_mbcnt_hi_u32_b32 v0, s1, v0
	s_mov_b64 s[2:3], s[46:47]
	v_mbcnt_lo_u32_b32 v1, s0, 0
	v_mbcnt_hi_u32_b32 v1, s0, v1
	s_mov_b64 s[0:1], s[46:47]
	v_or_b32_e32 v150, s82, v1
	s_load_dwordx2 s[0:1], s[0:1], 0x20
	v_ashrrev_i32_e32 v1, 31, v0
	v_lshlrev_b64 v[0:1], 2, v[0:1]
	v_mov_b32_e32 v8, 0
	v_mov_b32_e32 v12, 0
	s_waitcnt lgkmcnt(0)
	v_lshl_add_u64 v[2:3], s[0:1], 0, v[0:1]
	global_load_dword v4, v[2:3], off offset:1536
	global_load_dword v5, v[2:3], off offset:1792
	global_load_dword v6, v[2:3], off offset:2048
	s_mov_b64 s[0:1], s[46:47]
	global_load_dword v2, v[2:3], off offset:2304
	s_load_dwordx2 s[4:5], s[0:1], 0x40
	s_load_dwordx2 s[0:1], s[2:3], 0x28
	v_mov_b32_e32 v9, 0
	v_mov_b32_e32 v3, 0
	v_mov_b32_e32 v10, 0
	v_mov_b32_e32 v13, 0
	s_waitcnt lgkmcnt(0)
	v_lshl_add_u64 v[0:1], s[0:1], 0, v[0:1]
	global_load_dword v19, v[0:1], off offset:1024
	global_load_dword v20, v[0:1], off offset:1280
	global_load_dword v21, v[0:1], off offset:1536
	global_load_dword v22, v[0:1], off offset:1792
	v_mov_b32_e32 v16, 0
	v_mov_b32_e32 v11, 0
	v_mov_b32_e32 v14, 0
	v_mov_b32_e32 v17, 0
	v_mov_b32_e32 v15, 0
	v_mov_b32_e32 v18, 0
	v_mov_b32_e32 v7, 0
	s_mov_b64 s[0:1], s[46:47]
	s_mov_b32 s8, 0x3fb8aa3b
	s_load_dwordx2 s[0:1], s[0:1], 0x98
	s_mov_b64 s[2:3], s[46:47]
	s_waitcnt lgkmcnt(0)
	v_writelane_b32 v251, s0, 30
	s_nop 1
	v_writelane_b32 v251, s1, 31
	s_mov_b64 s[0:1], s[46:47]
	s_load_dwordx2 s[0:1], s[0:1], 0x98
	s_load_dwordx2 s[6:7], s[2:3], 0x98
	s_mov_b64 s[2:3], s[46:47]
	s_load_dwordx2 s[20:21], s[2:3], 0x30
	s_mov_b32 s2, 0xc2ce8ed0
	s_mov_b32 s3, 0x42b17218
	s_waitcnt vmcnt(7)
	v_and_b32_e32 v0, 0x7fffffff, v4
	s_nop 1
	v_mov_b32_dpp v8, v0 quad_perm:[1,0,3,2] row_mask:0xf bank_mask:0xf
	v_max_f32_e64 v1, |v4|, |v4|
	s_waitcnt vmcnt(6)
	v_and_b32_e32 v4, 0x7fffffff, v5
	v_max_f32_e32 v0, v8, v8
	v_max_f32_e32 v0, v1, v0
	v_mov_b32_dpp v12, v4 quad_perm:[1,0,3,2] row_mask:0xf bank_mask:0xf
	v_max_f32_e64 v5, |v5|, |v5|
	v_max_f32_e32 v4, v12, v12
	v_mov_b32_dpp v9, v0 quad_perm:[2,3,0,1] row_mask:0xf bank_mask:0xf
	s_waitcnt vmcnt(5)
	v_and_b32_e32 v23, 0x7fffffff, v6
	v_max_f32_e32 v1, v5, v4
	v_max_f32_e32 v4, v9, v9
	v_mov_b32_dpp v3, v23 quad_perm:[1,0,3,2] row_mask:0xf bank_mask:0xf
	v_max_f32_e32 v0, v0, v4
	v_max_f32_e64 v6, |v6|, |v6|
	v_max_f32_e32 v3, v3, v3
	v_mov_b32_dpp v10, v0 row_half_mirror row_mask:0xf bank_mask:0xf
	v_max_f32_e32 v3, v6, v3
	v_max_f32_e32 v4, v10, v10
	v_mov_b32_dpp v13, v1 quad_perm:[2,3,0,1] row_mask:0xf bank_mask:0xf
	v_mov_b32_dpp v16, v3 quad_perm:[2,3,0,1] row_mask:0xf bank_mask:0xf
	v_max_f32_e32 v0, v0, v4
	v_max_f32_e32 v5, v13, v13
	v_max_f32_e32 v6, v16, v16
	v_mov_b32_dpp v11, v0 row_mirror row_mask:0xf bank_mask:0xf
	v_max_f32_e32 v1, v1, v5
	v_max_f32_e32 v3, v3, v6
	v_max_f32_e32 v4, v11, v11
	v_mov_b32_dpp v14, v1 row_half_mirror row_mask:0xf bank_mask:0xf
	v_mov_b32_dpp v17, v3 row_half_mirror row_mask:0xf bank_mask:0xf
	v_max_f32_e32 v0, v0, v4
	v_max_f32_e32 v5, v14, v14
	v_max_f32_e32 v6, v17, v17
	v_mov_b32_e32 v4, v0
	v_max_f32_e32 v1, v1, v5
	v_max_f32_e32 v3, v3, v6
	v_permlane16_swap_b32_e32 v0, v4
	v_mov_b32_dpp v15, v1 row_mirror row_mask:0xf bank_mask:0xf
	v_mov_b32_dpp v18, v3 row_mirror row_mask:0xf bank_mask:0xf
	v_max_f32_e32 v4, v4, v4
	v_max_f32_e32 v0, v0, v0
	v_max_f32_e32 v5, v15, v15
	v_max_f32_e32 v6, v18, v18
	v_max_f32_e32 v0, v0, v4
	v_max_f32_e32 v1, v1, v5
	v_max_f32_e32 v3, v3, v6
	v_mov_b32_e32 v4, v0
	v_mov_b32_e32 v5, v1
	v_mov_b32_e32 v6, v3
	v_permlane32_swap_b32_e32 v0, v4
	v_permlane16_swap_b32_e32 v1, v5
	v_max_f32_e32 v4, v4, v4
	v_max_f32_e32 v0, v0, v0
	v_permlane16_swap_b32_e32 v3, v6
	v_max_f32_e32 v5, v5, v5
	v_max_f32_e32 v1, v1, v1
	v_max_f32_e32 v0, v0, v4
	v_max_f32_e32 v4, v6, v6
	v_max_f32_e32 v3, v3, v3
	v_max_f32_e32 v1, v1, v5
	v_max_f32_e32 v3, v3, v4
	v_mov_b32_e32 v5, v1
	v_mov_b32_e32 v4, v3
	s_nop 0
	v_permlane32_swap_b32_e32 v1, v5
	v_permlane32_swap_b32_e32 v3, v4
	v_max_f32_e32 v5, v5, v5
	v_max_f32_e32 v1, v1, v1
	v_max_f32_e32 v4, v4, v4
	v_max_f32_e32 v3, v3, v3
	v_max_f32_e32 v1, v1, v5
	v_max_f32_e32 v3, v3, v4
	s_waitcnt vmcnt(4)
; #define LAS __attribute__((address_space(3)))
; __device__ __forceinline__ float wave_sum(float v) { return xor32_sum(xor16_sum(row16_sum(v))); }
; #define AIN(i) (kargs()->in[i])
; #define AWS (kargs()->ws)
;             #define RFL(x) __uint_as_float(__builtin_amdgcn_readfirstlane(__float_as_uint(x)))
; __device__ __forceinline__ void attn_phase(const AttnCtx& C, unsigned* counter, LAS unsigned char* lds, int tid) {
;     LAS unsigned* ub = (LAS unsigned*)(lds + AL_U);
;     __syncthreads();
;     if (tid == 0) ub[0] = atomicAdd(counter, 1u);
; __global__ void __launch_bounds__(512, 2) fwd_megakernel(Args a) {
;     ...
;             for (int j = 0; j < 6; ++j) mg[j] = wave_max(fabsf(gq[j * 64 + lane_l]));
;             const float* rel = AIN(8) + l * 6 * 257;
;             float mr = 0.f;
;             for (int i = lane_l; i < 6 * 257; i += 64) mr = fmaxf(mr, fabsf(rel[i]));
;             mr = wave_max(mr);
;             const float* lp = AIN(5) + l * 4 * 64;
;             const float s01 = wave_sum(lp[lane_l] * lp[64 + lane_l]), s23 = wave_sum(lp[128 + lane_l] * lp[192 + lane_l]);
;             const float lam_init = (l == 0) ? 0.2f : (0.8f - 0.6f * 0.7408182206817179f);
;             AttnCtx C;
;             C.Z = P_Zb; C.O = P_HN; C.F2 = P_F2; C.rel = rel; C.subln = AIN(6) + l * 64;
;             C.lam = expf(s01) - expf(s23) + lam_init; C.oml = 1.0f - lam_init;
;             C.Mb0 = 8.0f * mg[0] * mg[1] * LOG2E * 1.02f + 1.0f; C.Mb1 = 8.0f * mg[2] * mg[3] * LOG2E * 1.02f + 1.0f; C.Mb2 = 8.0f * mg[4] * mg[5] * LOG2E * 1.02f + 1.0f + mr * LOG2E;
;     ...
;             C.lam = RFL(C.lam); C.oml = RFL(C.oml); C.Mb0 = RFL(C.Mb0); C.Mb1 = RFL(C.Mb1); C.Mb2 = RFL(C.Mb2);
;             attn_phase(C, (unsigned*)(AWS + WS_CTL) + CTL_Q + 16 * (1 + l), lds, tid_l);
	v_and_b32_e32 v4, 0x7fffffff, v2
	v_mov_b32_e32 v5, 0
	v_max_f32_e64 v2, |v2|, |v2|
	v_mul_f32_e32 v0, 0x41000000, v0
	v_mov_b32_dpp v5, v4 quad_perm:[1,0,3,2] row_mask:0xf bank_mask:0xf
	v_max_f32_e32 v4, v5, v5
	v_max_f32_e32 v2, v2, v4
	v_mov_b32_e32 v4, 0
	v_mov_b32_e32 v5, 0
	v_mul_f32_e32 v0, v0, v1
	v_mov_b32_dpp v4, v2 quad_perm:[2,3,0,1] row_mask:0xf bank_mask:0xf
	v_max_f32_e32 v4, v4, v4
	v_max_f32_e32 v2, v2, v4
	v_mov_b32_e32 v4, 0
	v_mul_f32_e32 v1, 0x41000000, v3
	v_readfirstlane_b32 s13, v0
	v_mov_b32_dpp v4, v2 row_half_mirror row_mask:0xf bank_mask:0xf
	v_max_f32_e32 v4, v4, v4
	v_max_f32_e32 v2, v2, v4
	v_mov_b32_e32 v4, 0
	s_nop 1
	v_mov_b32_dpp v4, v2 row_mirror row_mask:0xf bank_mask:0xf
	v_max_f32_e32 v4, v4, v4
	v_max_f32_e32 v2, v2, v4
	v_mov_b32_e32 v4, v2
	s_nop 1
	v_permlane16_swap_b32_e32 v2, v4
	v_max_f32_e32 v4, v4, v4
	v_max_f32_e32 v2, v2, v2
	v_max_f32_e32 v2, v2, v4
	v_mov_b32_e32 v4, v2
	s_nop 1
	v_permlane32_swap_b32_e32 v2, v4
	v_max_f32_e32 v4, v4, v4
	v_max_f32_e32 v2, v2, v2
	v_max_f32_e32 v2, v2, v4
	s_waitcnt vmcnt(2)
	v_mul_f32_e32 v4, v19, v20
	v_mul_f32_e32 v1, v1, v2
	s_nop 0
	v_mov_b32_dpp v5, v4 quad_perm:[1,0,3,2] row_mask:0xf bank_mask:0xf
	v_fmac_f32_e32 v5, v19, v20
	v_readfirstlane_b32 s12, v1
	s_nop 0
	v_add_f32_dpp v4, v5, v5 quad_perm:[2,3,0,1] row_mask:0xf bank_mask:0xf bound_ctrl:1
	s_nop 1
	v_add_f32_dpp v4, v4, v4 row_half_mirror row_mask:0xf bank_mask:0xf bound_ctrl:1
	s_nop 1
	v_add_f32_dpp v4, v4, v4 row_mirror row_mask:0xf bank_mask:0xf bound_ctrl:1
	v_mov_b32_e32 v5, v4
	s_nop 1
	v_permlane16_swap_b32_e32 v4, v5
	v_add_f32_e32 v4, v4, v5
	v_mov_b32_e32 v5, v4
	s_nop 1
	v_permlane32_swap_b32_e32 v4, v5
	v_add_f32_e32 v4, v4, v5
	s_waitcnt vmcnt(0)
	v_mul_f32_e32 v5, v21, v22
	v_cmp_ngt_f32_e32 vcc, s2, v4
	s_nop 0
	v_mov_b32_dpp v7, v5 quad_perm:[1,0,3,2] row_mask:0xf bank_mask:0xf
	v_fmac_f32_e32 v7, v21, v22
	s_nop 1
	v_add_f32_dpp v5, v7, v7 quad_perm:[2,3,0,1] row_mask:0xf bank_mask:0xf bound_ctrl:1
	s_nop 1
	v_add_f32_dpp v5, v5, v5 row_half_mirror row_mask:0xf bank_mask:0xf bound_ctrl:1
	s_nop 1
	v_add_f32_dpp v5, v5, v5 row_mirror row_mask:0xf bank_mask:0xf bound_ctrl:1
	v_mov_b32_e32 v6, v5
	s_nop 1
	v_permlane16_swap_b32_e32 v5, v6
	v_add_f32_e32 v5, v5, v6
	v_mov_b32_e32 v6, v5
	s_nop 1
	v_permlane32_swap_b32_e32 v5, v6
	v_add_f32_e32 v5, v5, v6
	v_mul_f32_e32 v6, 0x3fb8aa3b, v4
	v_fma_f32 v7, v4, s8, -v6
	v_rndne_f32_e32 v8, v6
	v_fmac_f32_e32 v7, 0x32a5705f, v4
	v_sub_f32_e32 v6, v6, v8
	v_add_f32_e32 v6, v6, v7
	v_exp_f32_e32 v6, v6
	v_cvt_i32_f32_e32 v7, v8
	v_ldexp_f32 v6, v6, v7
	v_mul_f32_e32 v7, 0x3fb8aa3b, v5
	v_fma_f32 v8, v5, s8, -v7
	v_rndne_f32_e32 v9, v7
	v_fmac_f32_e32 v8, 0x32a5705f, v5
	v_sub_f32_e32 v7, v7, v9
	v_add_f32_e32 v7, v7, v8
	v_exp_f32_e32 v7, v7
	v_cvt_i32_f32_e32 v8, v9
	v_cndmask_b32_e32 v6, 0, v6, vcc
	v_mov_b32_e32 v9, 0x7f800000
	v_cmp_nlt_f32_e32 vcc, s3, v4
	s_nop 1
	v_cndmask_b32_e32 v4, v9, v6, vcc
	v_ldexp_f32 v6, v7, v8
	v_cmp_ngt_f32_e32 vcc, s2, v5
	s_nop 1
	v_cndmask_b32_e32 v6, 0, v6, vcc
	v_cmp_nlt_f32_e32 vcc, s3, v5
	s_mov_b64 s[2:3], s[46:47]
	s_load_dwordx2 s[2:3], s[2:3], 0x98
	v_cndmask_b32_e32 v5, v9, v6, vcc
	v_sub_f32_e32 v4, v4, v5
	v_cmp_eq_u32_e32 vcc, 0, v150
	v_readfirstlane_b32 s14, v4
	s_waitcnt lgkmcnt(0)
	s_add_u32 s2, s2, 0x3880
	s_addc_u32 s3, s3, 0
	v_writelane_b32 v251, s2, 17
	s_barrier
	s_nop 0
	v_writelane_b32 v251, s3, 18
	s_and_saveexec_b64 s[8:9], vcc
	s_cbranch_execz .LBB0_1275
	s_mov_b64 s[2:3], exec
	v_mbcnt_lo_u32_b32 v0, s2, 0
	v_mbcnt_hi_u32_b32 v0, s3, v0
	v_cmp_eq_u32_e32 vcc, 0, v0
	s_and_saveexec_b64 s[10:11], vcc
	s_cbranch_execz .LBB0_1274
	s_bcnt1_i32_b64 s2, s[2:3]
	v_mov_b32_e32 v2, s2
	v_readlane_b32 s2, v251, 17
	v_mov_b32_e32 v1, 0
	v_readlane_b32 s3, v251, 18
	s_nop 4
	global_atomic_add v1, v1, v2, s[2:3] sc0

; __device__ __forceinline__ unsigned pk2(float lo, float hi) { f32x2_t v = {lo, hi}; bf16x2_t b = __builtin_convertvector(v, bf16x2_t); return __builtin_bit_cast(unsigned, b); }
; __device__ __forceinline__ void attn_phase(const AttnCtx& C, unsigned* counter, LAS unsigned char* lds, int tid) {
;     ...
;     if (tid == 0) ub[0] = atomicAdd(counter, 1u);
;     for (;;) {
;         __syncthreads();
; __global__ void __launch_bounds__(512, 2) fwd_megakernel(Args a) {
;     ...
;             const f32x4 v0 = *(const f32x4*)(pp_ + 8 * i), v1 = *(const f32x4*)(pp_ + 8 * i + 4);
;             u32x4 w; w.x = pk2(v0[0], v0[1]); w.y = pk2(v0[2], v0[3]); w.z = pk2(v1[0], v1[1]); w.w = pk2(v1[2], v1[3]);
;             *(u32x4*)(pb_ + 8 * i) = w;
.LBB0_1276:
	s_or_b64 exec, exec, s[0:1]
	s_load_dwordx2 s[100:101], s[46:47], 0x98
	s_waitcnt lgkmcnt(0)
	s_add_u32 s100, s100, 0x3804000
	s_addc_u32 s101, s101, 0
	s_waitcnt vmcnt(40)
	v_cmp_gt_u32_e32 vcc, 0x200000, v248
	s_and_saveexec_b64 s[98:99], vcc
	v_cvt_pk_bf16_f32 v232, v232, v233
	v_cvt_pk_bf16_f32 v233, v234, v235
	v_cvt_pk_bf16_f32 v234, v236, v237
	v_cvt_pk_bf16_f32 v235, v238, v239
	v_lshlrev_b32_e32 v250, 4, v248
	global_store_dwordx4 v250, v[232:235], s[100:101]
	s_mov_b64 exec, s[98:99]
	v_cmp_gt_u32_e32 vcc, 0x200000, v249
	s_and_saveexec_b64 s[98:99], vcc
	v_cvt_pk_bf16_f32 v240, v240, v241
	v_cvt_pk_bf16_f32 v241, v242, v243
	v_cvt_pk_bf16_f32 v242, v244, v245
	v_cvt_pk_bf16_f32 v243, v246, v247
	v_lshlrev_b32_e32 v250, 4, v249
	global_store_dwordx4 v250, v[240:243], s[100:101]
	s_mov_b64 exec, s[98:99]
	s_mov_b64 s[0:1], 0

; #define K_TID ((wave_s << 6) | lane_fresh())
; __device__ __forceinline__ void attn_phase(const AttnCtx& C, unsigned* counter, LAS unsigned char* lds, int tid) {
;     ...
;         __syncthreads();
;         const int u = (int)ub[0];
;         if (u >= ATT_UNITS) break;
;         int ty, ub_, uh, uq;
;         if (u < 256) { ty = 0; ub_ = (u & 31) >> 2; uh = u & 3; uq = 15 - (u >> 5); }
;         else if (u < 1280) { const int v = u - 256, q = 7 - (v >> 7), wv = v & 127;
;             if (wv < 32) { ty = 0; ub_ = wv >> 2; uh = wv & 3; uq = q; }
;             else if (wv < 80) { ty = 1; ub_ = (wv - 32) / 6; uh = (wv - 32) % 6; uq = 2 * q + 1; }
;             else { ty = 1; ub_ = (wv - 80) / 6; uh = (wv - 80) % 6; uq = 2 * q; } }
;         else { const int v = u - 1280; ty = 2; ub_ = (v % 48) / 6; uh = (v % 48) % 6; uq = 15 - v / 48; }
; __global__ void __launch_bounds__(512, 2) fwd_megakernel(Args a) {
;     ...
;         for (size_t i = (size_t)bx * 512 + K_TID; i < n8; i += (size_t)G * 512) {
;             const f32x4 v0 = *(const f32x4*)(pp_ + 8 * i), v1 = *(const f32x4*)(pp_ + 8 * i + 4);
.LBB0_1278:
	s_waitcnt lgkmcnt(0)
	s_barrier
	ds_read_b32 v0, v154
	s_movk_i32 s0, 0x7ff
	s_waitcnt lgkmcnt(0)
	v_cmp_lt_i32_e32 vcc, s0, v0
	v_readfirstlane_b32 s2, v0
	s_mov_b64 s[0:1], -1
	s_cbranch_vccnz .LBB0_1277
	s_load_dwordx2 s[100:101], s[46:47], 0x8
	v_mov_b32_e32 v248, v212
	v_add_u32_e32 v249, v212, v211
	v_add_u32_e32 v212, v249, v211
	v_cmp_gt_u32_e32 vcc, 0x200000, v248
	s_waitcnt lgkmcnt(0)
	s_and_saveexec_b64 s[98:99], vcc
	v_lshlrev_b32_e32 v250, 5, v248
	global_load_dwordx4 v[232:235], v250, s[100:101]
	global_load_dwordx4 v[236:239], v250, s[100:101] offset:16
	s_mov_b64 exec, s[98:99]
	v_cmp_gt_u32_e32 vcc, 0x200000, v249
	s_and_saveexec_b64 s[98:99], vcc
	v_lshlrev_b32_e32 v250, 5, v249
	global_load_dwordx4 v[240:243], v250, s[100:101]
	global_load_dwordx4 v[244:247], v250, s[100:101] offset:16
	s_mov_b64 exec, s[98:99]
	s_cmpk_gt_i32 s2, 0xff
	s_cbranch_scc0 .LBB0_1292
	s_cmpk_gt_u32 s2, 0x4ff
	s_cbranch_scc0 .LBB0_1282
	s_add_i32 s0, s2, 0xfb00
	s_and_b32 s1, s0, 0xffff
	s_mul_i32 s1, s1, 0xaaab
	s_lshr_b32 s1, s1, 21
	s_mul_i32 s3, s1, 48
	s_sub_i32 s0, s0, s3
	s_mul_i32 s3, s0, 0xab
	s_bfe_u32 s24, s3, 0x6000a
	s_mul_i32 s3, s24, 6
	s_sub_i32 s0, s0, s3
	s_and_b32 s78, s0, 0xff
	s_sub_i32 s6, 15, s1
	s_mov_b64 s[0:1], 0

; __device__ __forceinline__ unsigned pk2(float lo, float hi) { f32x2_t v = {lo, hi}; bf16x2_t b = __builtin_convertvector(v, bf16x2_t); return __builtin_bit_cast(unsigned, b); }
; #define K_TID ((wave_s << 6) | lane_fresh())
; __device__ __forceinline__ void xcd_barrier(const XcdBarrier& b, const bool xb_is_leader) {
;     asm volatile("s_waitcnt vmcnt(0)" ::: "memory");
;     __syncthreads();
;     if (xb_is_leader) {
;         unsigned* bar = b.bar;
;         __builtin_amdgcn_s_waitcnt(0);
;         unsigned nloc = b.st[0], nx = b.st[1];
;         if (nloc == 0u) { xcd_barrier_complete(bar, b.x, nloc, nx); b.st[0] = nloc; b.st[1] = nx; }
; __global__ void __launch_bounds__(512, 2) fwd_megakernel(Args a) {
;     ...
;         for (size_t i = (size_t)bx * 512 + K_TID; i < n8; i += (size_t)G * 512) {
;             const f32x4 v0 = *(const f32x4*)(pp_ + 8 * i), v1 = *(const f32x4*)(pp_ + 8 * i + 4);
;             u32x4 w; w.x = pk2(v0[0], v0[1]); w.y = pk2(v0[2], v0[3]); w.z = pk2(v1[0], v1[1]); w.w = pk2(v1[2], v1[3]);
;             *(u32x4*)(pb_ + 8 * i) = w;
.LBB0_1388:
.Lpd_rem_1:
	v_cmp_gt_u32_e32 vcc, 0x200000, v212
	s_and_saveexec_b64 s[98:99], vcc
	s_cbranch_execz .Lpd_done_1
	s_load_dwordx2 s[100:101], s[46:47], 0x8
	v_lshlrev_b32_e32 v250, 5, v212
	s_waitcnt lgkmcnt(0)
	global_load_dwordx4 v[232:235], v250, s[100:101]
	global_load_dwordx4 v[236:239], v250, s[100:101] offset:16
	s_load_dwordx2 s[100:101], s[46:47], 0x98
	s_waitcnt lgkmcnt(0)
	s_add_u32 s100, s100, 0x3804000
	s_addc_u32 s101, s101, 0
	s_waitcnt vmcnt(0)
	v_cvt_pk_bf16_f32 v232, v232, v233
	v_cvt_pk_bf16_f32 v233, v234, v235
	v_cvt_pk_bf16_f32 v234, v236, v237
	v_cvt_pk_bf16_f32 v235, v238, v239
	v_lshlrev_b32_e32 v250, 4, v212
	global_store_dwordx4 v250, v[232:235], s[100:101]
	v_add_u32_e32 v212, v212, v211
	s_mov_b64 exec, s[98:99]
	s_branch .Lpd_rem_1
.Lpd_done_1:
	s_mov_b64 exec, s[98:99]
	s_mov_b32 s0, -1
	v_readlane_b32 s84, v251, 26
	v_mbcnt_lo_u32_b32 v0, s0, 0
	v_mbcnt_hi_u32_b32 v0, s0, v0
	s_setprio 0
	s_waitcnt vmcnt(0)
	s_waitcnt lgkmcnt(0)
	v_or_b32_e32 v0, s84, v0
	v_cmp_eq_u32_e32 vcc, 0, v0
	s_barrier
	s_and_saveexec_b64 s[4:5], vcc
	v_readlane_b32 s88, v251, 37
	v_readlane_b32 s62, v251, 5
	v_readlane_b32 s85, v251, 27
	v_readlane_b32 s89, v251, 38
	v_readlane_b32 s90, v251, 28
	v_readlane_b32 s91, v251, 3
	v_readlane_b32 s63, v251, 6
	s_cbranch_execz .LBB0_1440
	v_mov_b32_e32 v0, 0x22000
	s_waitcnt vmcnt(0) expcnt(0) lgkmcnt(0)
	ds_read_b32 v2, v0
	v_mov_b32_e32 v0, 0x22004
	ds_read_b32 v0, v0
	s_waitcnt lgkmcnt(1)
	v_cmp_ne_u32_e32 vcc, 0, v2
	s_cbranch_vccnz .LBB0_1404
	v_readlane_b32 s0, v251, 0
	v_readlane_b32 s1, v251, 1
	v_readlane_b32 s2, v251, 2
	s_mul_i32 s2, s1, s2
	s_mul_i32 s2, s2, s0
	s_add_u32 s0, s76, 0x1000
	s_addc_u32 s1, s77, 0
	s_add_u32 s6, s76, 0x1100
	s_addc_u32 s7, s77, 0
	s_add_u32 s8, s76, 0x1200
	s_addc_u32 s9, s77, 0
	s_add_u32 s10, s76, 0x1300
	s_addc_u32 s11, s77, 0
	s_mov_b32 s3, 1
	v_mov_b32_e32 v16, 0
	s_branch .LBB0_1392
